# attention softmax: scalar v_fmamk pairs on adjacent score registers packed into v_pk_fma_f32 (bit-identical), both attention loops; on top of sc1 GEMM epilogue stores
# speedup vs baseline: 1.0073x; 1.0073x over previous
.LBB0_396:
	s_mov_b32 s100, 0x3e38aa3b
	s_barrier
	s_and_saveexec_b64 s[8:9], s[4:5]
	s_cbranch_execz .LBB0_418
	s_and_b64 vcc, exec, s[6:7]
	s_cbranch_vccz .LBB0_407
	s_mov_b64 s[12:13], 0
	v_mov_b32_e32 v0, -1
	s_and_saveexec_b64 s[10:11], s[30:31]
	s_cbranch_execz .LBB0_402
	s_mov_b64 s[14:15], exec
	v_mbcnt_lo_u32_b32 v0, s14, 0
	v_mbcnt_hi_u32_b32 v0, s15, v0
	v_cmp_eq_u32_e32 vcc, 0, v0
	s_and_saveexec_b64 s[12:13], vcc
	s_cbranch_execz .LBB0_401
	s_bcnt1_i32_b64 s2, s[14:15]
	v_mov_b32_e32 v1, s2
	global_atomic_add v1, v149, v1, s[90:91] offset:4 sc0

.LBB0_424:
	v_add_u32_e32 v103, v98, v95
	s_barrier
	s_waitcnt vmcnt(3)
	ds_write_b128 v102, v[16:19]
	s_waitcnt vmcnt(2)
	ds_write_b128 v102, v[20:23] offset:9216
	s_waitcnt vmcnt(1)
	ds_write_b128 v100, v[24:27]
	s_waitcnt vmcnt(0)
	ds_write_b128 v100, v[28:31] offset:9216
	s_waitcnt lgkmcnt(0)
	s_barrier
	ds_read_b128 v[84:87], v103 offset:6912
	ds_read_b128 v[64:67], v103
	s_waitcnt lgkmcnt(1)
	v_mfma_f32_16x16x32_bf16 v[116:119], v[84:87], v[8:11], 0
	ds_read_b128 v[72:75], v103 offset:2304
	ds_read_b128 v[80:83], v103 offset:4608
	v_mov_b32_e32 v128, v147
	v_mfma_f32_16x16x32_bf16 v[120:123], v[84:87], v[12:15], 0
	ds_read_b128 v[84:87], v103 offset:64
	v_mov_b32_e32 v130, v146
	v_lshl_add_u64 v[16:17], v[106:107], 0, v[148:149]
	s_waitcnt lgkmcnt(3)
	v_mfma_f32_16x16x32_bf16 v[68:71], v[64:67], v[8:11], 0
	v_lshl_add_u64 v[20:21], v[110:111], 0, v[148:149]
	v_lshl_add_u64 v[24:25], v[104:105], 0, v[148:149]
	v_lshl_add_u64 v[28:29], v[108:109], 0, v[148:149]
	v_mfma_f32_16x16x32_bf16 v[64:67], v[64:67], v[12:15], 0
	global_load_dwordx4 v[16:19], v[16:17], off
	s_add_i32 s2, s2, -1
	global_load_dwordx4 v[20:23], v[20:21], off
	s_waitcnt lgkmcnt(0)
	v_mfma_f32_16x16x32_bf16 v[124:127], v[84:87], v[0:3], v[68:71]
	global_load_dwordx4 v[24:27], v[24:25], off
	v_lshl_add_u64 v[104:105], v[104:105], 0, s[72:73]
	global_load_dwordx4 v[28:31], v[28:29], off
	v_mfma_f32_16x16x32_bf16 v[84:87], v[84:87], v[4:7], v[64:67]
	v_lshl_add_u64 v[106:107], v[106:107], 0, s[72:73]
	v_lshl_add_u64 v[108:109], v[108:109], 0, s[52:53]
	v_lshl_add_u64 v[110:111], v[110:111], 0, s[52:53]
	ds_read_b128 v[64:67], v103 offset:2368
	v_mfma_f32_16x16x32_bf16 v[76:79], v[72:75], v[8:11], 0
	s_cmp_lg_u32 s2, 0
	v_mfma_f32_16x16x32_bf16 v[72:75], v[72:75], v[12:15], 0
	s_waitcnt lgkmcnt(0)
	v_mfma_f32_16x16x32_bf16 v[140:143], v[64:67], v[0:3], v[76:79]
	v_mfma_f32_16x16x32_bf16 v[72:75], v[64:67], v[4:7], v[72:75]
	ds_read_b128 v[64:67], v103 offset:4672
	v_mfma_f32_16x16x32_bf16 v[112:115], v[80:83], v[8:11], 0
	v_mfma_f32_16x16x32_bf16 v[80:83], v[80:83], v[12:15], 0
	s_waitcnt lgkmcnt(0)
	v_mfma_f32_16x16x32_bf16 v[150:153], v[64:67], v[0:3], v[112:115]
	v_mfma_f32_16x16x32_bf16 v[76:79], v[64:67], v[4:7], v[80:83]
	ds_read_b128 v[64:67], v103 offset:6976
	s_waitcnt lgkmcnt(0)
	v_mfma_f32_16x16x32_bf16 v[154:157], v[64:67], v[0:3], v[116:119]
	v_mfma_f32_16x16x32_bf16 v[80:83], v[64:67], v[4:7], v[120:123]
	v_max3_f32 v64, v124, s38, v125
	v_max3_f32 v64, v64, v126, v127
	v_max3_f32 v64, v64, v140, v141
	v_max3_f32 v64, v64, v142, v143
	v_max3_f32 v64, v64, v150, v151
	v_max3_f32 v64, v64, v152, v153
	s_nop 0
	v_max3_f32 v64, v64, v154, v155
	v_max3_f32 v64, v64, v156, v157
	ds_bpermute_b32 v65, v145, v64
	s_waitcnt lgkmcnt(0)
	v_max_f32_e32 v65, v65, v65
	v_max_f32_e32 v64, v64, v65
	ds_bpermute_b32 v65, v99, v64
	s_waitcnt lgkmcnt(0)
	v_max3_f32 v147, v128, v64, v65
	v_sub_f32_e32 v64, v128, v147
	v_mul_f32_e32 v64, 0x3e38aa3b, v64
	v_exp_f32_e32 v144, v64
	s_nop 0
	v_pk_mul_f32 v[64:65], v[52:53], v[144:145] op_sel_hi:[1,0]
	v_pk_mul_f32 v[52:53], v[56:57], v[144:145] op_sel_hi:[1,0]
	v_mul_f32_e32 v56, 0xbe38aa3b, v147
	v_pk_fma_f32 v[244:245], v[124:125], s[100:101], v[56:57] op_sel_hi:[1,0,0]
	v_exp_f32_e32 v129, v244
	v_exp_f32_e32 v131, v245
	v_pk_fma_f32 v[246:247], v[126:127], s[100:101], v[56:57] op_sel_hi:[1,0,0]
	v_exp_f32_e32 v133, v246
	v_exp_f32_e32 v135, v247
	v_pk_fma_f32 v[248:249], v[140:141], s[100:101], v[56:57] op_sel_hi:[1,0,0]
	v_exp_f32_e32 v137, v248
	v_exp_f32_e32 v139, v249
	v_pk_fma_f32 v[250:251], v[142:143], s[100:101], v[56:57] op_sel_hi:[1,0,0]
	v_exp_f32_e32 v141, v250
	v_exp_f32_e32 v143, v251
	v_pk_fma_f32 v[244:245], v[150:151], s[100:101], v[56:57] op_sel_hi:[1,0,0]
	v_exp_f32_e32 v113, v244
	v_exp_f32_e32 v115, v245
	v_pk_fma_f32 v[246:247], v[152:153], s[100:101], v[56:57] op_sel_hi:[1,0,0]
	v_exp_f32_e32 v117, v246
	v_exp_f32_e32 v119, v247
	v_pk_fma_f32 v[248:249], v[154:155], s[100:101], v[56:57] op_sel_hi:[1,0,0]
	v_exp_f32_e32 v121, v248
	v_exp_f32_e32 v123, v249
	v_fmamk_f32 v57, v156, 0x3e38aa3b, v56
	v_fmac_f32_e32 v56, 0x3e38aa3b, v157
	v_exp_f32_e32 v127, v56
	v_max3_f32 v56, v84, s38, v85
	v_max3_f32 v56, v56, v86, v87
	v_max3_f32 v56, v56, v72, v73
	v_max3_f32 v56, v56, v74, v75
	v_max3_f32 v56, v56, v76, v77
	v_max3_f32 v56, v56, v78, v79
	v_max3_f32 v56, v56, v80, v81
	v_max3_f32 v56, v56, v82, v83
	v_exp_f32_e32 v125, v57
	ds_bpermute_b32 v57, v145, v56
	v_pk_mul_f32 v[66:67], v[54:55], v[144:145] op_sel_hi:[1,0]
	v_pk_mul_f32 v[54:55], v[58:59], v[144:145] op_sel_hi:[1,0]
	v_pk_mul_f32 v[70:71], v[50:51], v[144:145] op_sel_hi:[1,0]
	v_pk_mul_f32 v[68:69], v[48:49], v[144:145] op_sel_hi:[1,0]
	s_waitcnt lgkmcnt(0)
	v_max_f32_e32 v57, v57, v57
	v_max_f32_e32 v56, v56, v57
	ds_bpermute_b32 v57, v99, v56
	v_pk_mul_f32 v[50:51], v[62:63], v[144:145] op_sel_hi:[1,0]
	v_pk_mul_f32 v[48:49], v[60:61], v[144:145] op_sel_hi:[1,0]
	s_waitcnt lgkmcnt(0)
	v_max3_f32 v146, v130, v56, v57
	v_sub_f32_e32 v56, v130, v146
	v_mul_f32_e32 v56, 0x3e38aa3b, v56
	v_exp_f32_e32 v150, v56
	s_nop 0
	v_pk_mul_f32 v[58:59], v[38:39], v[150:151] op_sel_hi:[1,0]
	v_pk_mul_f32 v[38:39], v[42:43], v[150:151] op_sel_hi:[1,0]
	v_mul_f32_e32 v42, 0xbe38aa3b, v146
	v_pk_mul_f32 v[56:57], v[36:37], v[150:151] op_sel_hi:[1,0]
	v_pk_mul_f32 v[36:37], v[40:41], v[150:151] op_sel_hi:[1,0]
	v_pk_fma_f32 v[250:251], v[84:85], s[100:101], v[42:43] op_sel_hi:[1,0,0]
	v_exp_f32_e32 v128, v250
	v_exp_f32_e32 v130, v251
	v_pk_fma_f32 v[244:245], v[86:87], s[100:101], v[42:43] op_sel_hi:[1,0,0]
	v_exp_f32_e32 v132, v244
	v_exp_f32_e32 v134, v245
	v_pk_fma_f32 v[246:247], v[72:73], s[100:101], v[42:43] op_sel_hi:[1,0,0]
	v_exp_f32_e32 v136, v246
	v_exp_f32_e32 v138, v247
	v_pk_add_f32 v[40:41], v[128:129], 0 op_sel_hi:[1,0]
	v_pk_fma_f32 v[248:249], v[74:75], s[100:101], v[42:43] op_sel_hi:[1,0,0]
	v_pk_add_f32 v[40:41], v[130:131], v[40:41]
	v_exp_f32_e32 v140, v248
	v_pk_add_f32 v[40:41], v[132:133], v[40:41]
	v_pk_add_f32 v[40:41], v[134:135], v[40:41]
	v_exp_f32_e32 v142, v249
	v_pk_fma_f32 v[250:251], v[76:77], s[100:101], v[42:43] op_sel_hi:[1,0,0]
	v_pk_add_f32 v[40:41], v[136:137], v[40:41]
	v_exp_f32_e32 v112, v250
	v_pk_add_f32 v[40:41], v[138:139], v[40:41]
	v_exp_f32_e32 v114, v251
	v_pk_fma_f32 v[244:245], v[78:79], s[100:101], v[42:43] op_sel_hi:[1,0,0]
	v_exp_f32_e32 v116, v244
	v_pk_add_f32 v[40:41], v[140:141], v[40:41]
	v_exp_f32_e32 v118, v245
	v_pk_fma_f32 v[246:247], v[80:81], s[100:101], v[42:43] op_sel_hi:[1,0,0]
	v_pk_add_f32 v[40:41], v[142:143], v[40:41]
	v_add_u32_e32 v72, 0x2000, v101
	v_pk_mul_f32 v[62:63], v[34:35], v[150:151] op_sel_hi:[1,0]
	v_pk_mul_f32 v[60:61], v[32:33], v[150:151] op_sel_hi:[1,0]
	v_pk_mul_f32 v[34:35], v[46:47], v[150:151] op_sel_hi:[1,0]
	v_pk_mul_f32 v[32:33], v[44:45], v[150:151] op_sel_hi:[1,0]
	v_exp_f32_e32 v120, v246
	v_pk_add_f32 v[40:41], v[112:113], v[40:41]
	ds_read2_b64 v[44:47], v72 offset0:128 offset1:132
	v_exp_f32_e32 v122, v247
	v_fmamk_f32 v43, v82, 0x3e38aa3b, v42
	v_pk_add_f32 v[40:41], v[114:115], v[40:41]
	v_exp_f32_e32 v124, v43
	v_fmac_f32_e32 v42, 0x3e38aa3b, v83
	v_pk_add_f32 v[40:41], v[116:117], v[40:41]
	v_exp_f32_e32 v126, v42
	v_pk_add_f32 v[40:41], v[118:119], v[40:41]
	v_mov_b32_e32 v151, v144
	v_pk_add_f32 v[40:41], v[120:121], v[40:41]
	v_cvt_pk_bf16_f32 v43, v141, v143
	v_pk_add_f32 v[40:41], v[122:123], v[40:41]
	v_cvt_pk_bf16_f32 v42, v137, v139
	v_pk_add_f32 v[40:41], v[124:125], v[40:41]
	v_cvt_pk_bf16_f32 v81, v140, v142
	v_pk_add_f32 v[40:41], v[126:127], v[40:41]
	v_cvt_pk_bf16_f32 v80, v136, v138
	v_pk_fma_f32 v[96:97], v[96:97], v[150:151], v[40:41]
	v_cvt_pk_bf16_f32 v41, v133, v135
	v_cvt_pk_bf16_f32 v40, v129, v131
	v_cvt_pk_bf16_f32 v79, v132, v134
	v_cvt_pk_bf16_f32 v78, v128, v130
	s_waitcnt lgkmcnt(0)
	v_mfma_f32_16x16x32_bf16 v[74:77], v[44:47], v[40:43], v[68:71]
	v_cvt_pk_bf16_f32 v135, v125, v127
	v_cvt_pk_bf16_f32 v134, v121, v123
	v_cvt_pk_bf16_f32 v133, v117, v119
	v_add_u32_e32 v70, 0x2800, v101
	v_mfma_f32_16x16x32_bf16 v[44:47], v[44:47], v[78:81], v[60:63]
	v_add_u32_e32 v69, 0x3000, v101
	v_add_u32_e32 v68, 0x3800, v101
	v_cvt_pk_bf16_f32 v132, v113, v115
	ds_read2_b64 v[60:63], v70 offset0:160 offset1:164
	s_waitcnt lgkmcnt(0)
	v_mfma_f32_16x16x32_bf16 v[64:67], v[60:63], v[40:43], v[64:67]
	v_mfma_f32_16x16x32_bf16 v[56:59], v[60:63], v[78:81], v[56:59]
	ds_read2_b64 v[60:63], v69 offset0:192 offset1:196
	s_waitcnt lgkmcnt(0)
	v_mfma_f32_16x16x32_bf16 v[82:85], v[60:63], v[40:43], v[52:55]
	v_mfma_f32_16x16x32_bf16 v[60:63], v[60:63], v[78:81], v[36:39]
	s_nop 2
	ds_read2_b64 v[36:39], v68 offset0:224 offset1:228
	s_waitcnt lgkmcnt(0)
	v_mfma_f32_16x16x32_bf16 v[78:81], v[36:39], v[78:81], v[32:35]
	s_nop 2
	ds_read2_b64 v[32:35], v72 offset0:136 offset1:140
	v_mfma_f32_16x16x32_bf16 v[128:131], v[36:39], v[40:43], v[48:51]
	ds_read2_b64 v[36:39], v70 offset0:168 offset1:172
	ds_read2_b64 v[40:43], v69 offset0:200 offset1:204
	s_waitcnt lgkmcnt(2)
	v_mfma_f32_16x16x32_bf16 v[48:51], v[32:35], v[132:135], v[74:77]
	s_nop 2
	v_cvt_pk_bf16_f32 v77, v124, v126
	v_cvt_pk_bf16_f32 v76, v120, v122
	v_cvt_pk_bf16_f32 v75, v116, v118
	v_cvt_pk_bf16_f32 v74, v112, v114
	s_waitcnt lgkmcnt(1)
	v_mfma_f32_16x16x32_bf16 v[52:55], v[36:39], v[132:135], v[64:67]
	v_mfma_f32_16x16x32_bf16 v[32:35], v[32:35], v[74:77], v[44:47]
	s_nop 2
	ds_read2_b64 v[44:47], v68 offset0:232 offset1:236
	v_mfma_f32_16x16x32_bf16 v[36:39], v[36:39], v[74:77], v[56:59]
	s_waitcnt lgkmcnt(1)
	v_mfma_f32_16x16x32_bf16 v[56:59], v[40:43], v[132:135], v[82:85]
	v_mfma_f32_16x16x32_bf16 v[40:43], v[40:43], v[74:77], v[60:63]
	s_waitcnt lgkmcnt(0)
	v_mfma_f32_16x16x32_bf16 v[60:63], v[44:47], v[132:135], v[128:131]
	v_mfma_f32_16x16x32_bf16 v[44:47], v[44:47], v[74:77], v[78:81]
	s_cbranch_scc1 .LBB0_424
	s_barrier
	s_waitcnt vmcnt(3)
	ds_write_b128 v102, v[16:19]
	s_waitcnt vmcnt(2)
	ds_write_b128 v102, v[20:23] offset:9216
	s_waitcnt vmcnt(1)
	ds_write_b128 v100, v[24:27]
	s_waitcnt vmcnt(0)
	ds_write_b128 v100, v[28:31] offset:9216
	s_waitcnt lgkmcnt(0)
	s_barrier
	ds_read_b128 v[16:19], v103
	ds_read_b128 v[24:27], v103 offset:2304
	ds_read_b128 v[64:67], v103 offset:4608
	ds_read_b128 v[78:81], v103 offset:6912
	s_waitcnt lgkmcnt(3)
	v_mfma_f32_16x16x32_bf16 v[20:23], v[16:19], v[8:11], 0
	v_mov_b32_e32 v95, v149
	s_mov_b64 s[8:9], 0
	v_mfma_f32_16x16x32_bf16 v[16:19], v[16:19], v[12:15], 0
	s_waitcnt lgkmcnt(2)
	v_mfma_f32_16x16x32_bf16 v[28:31], v[24:27], v[8:11], 0
	v_mfma_f32_16x16x32_bf16 v[24:27], v[24:27], v[12:15], 0
	s_waitcnt lgkmcnt(1)
	v_mfma_f32_16x16x32_bf16 v[74:77], v[64:67], v[8:11], 0
	v_mfma_f32_16x16x32_bf16 v[64:67], v[64:67], v[12:15], 0
	s_waitcnt lgkmcnt(0)
	v_mfma_f32_16x16x32_bf16 v[8:11], v[78:81], v[8:11], 0
	v_mfma_f32_16x16x32_bf16 v[12:15], v[78:81], v[12:15], 0
	ds_read_b128 v[78:81], v103 offset:64
	s_waitcnt lgkmcnt(0)
	v_mfma_f32_16x16x32_bf16 v[82:85], v[78:81], v[0:3], v[20:23]
	v_mfma_f32_16x16x32_bf16 v[20:23], v[78:81], v[4:7], v[16:19]
	s_nop 2
	ds_read_b128 v[16:19], v103 offset:2368
	s_waitcnt lgkmcnt(0)
	v_mfma_f32_16x16x32_bf16 v[28:31], v[16:19], v[0:3], v[28:31]
	v_mfma_f32_16x16x32_bf16 v[16:19], v[16:19], v[4:7], v[24:27]
	s_nop 2
	ds_read_b128 v[24:27], v103 offset:4672
	s_waitcnt lgkmcnt(0)
	v_mfma_f32_16x16x32_bf16 v[74:77], v[24:27], v[0:3], v[74:77]
	v_mfma_f32_16x16x32_bf16 v[24:27], v[24:27], v[4:7], v[64:67]
	s_nop 2
	ds_read_b128 v[64:67], v103 offset:6976
	s_waitcnt lgkmcnt(0)
	v_mfma_f32_16x16x32_bf16 v[78:81], v[64:67], v[0:3], v[8:11]
	v_max3_f32 v0, v82, s38, v83
	v_max3_f32 v0, v0, v84, v85
	v_max3_f32 v0, v0, v28, v29
	v_max3_f32 v0, v0, v30, v31
	v_max3_f32 v0, v0, v74, v75
	v_max3_f32 v0, v0, v76, v77
	s_nop 1
	v_max3_f32 v0, v0, v78, v79
	v_max3_f32 v0, v0, v80, v81
	ds_bpermute_b32 v1, v145, v0
	v_mfma_f32_16x16x32_bf16 v[64:67], v[64:67], v[4:7], v[12:15]
	s_waitcnt lgkmcnt(0)
	v_max_f32_e32 v1, v1, v1
	v_max_f32_e32 v0, v0, v1
	ds_bpermute_b32 v1, v99, v0
	s_waitcnt lgkmcnt(0)
	v_max3_f32 v71, v147, v0, v1
	v_sub_f32_e32 v0, v147, v71
	v_mul_f32_e32 v0, 0x3e38aa3b, v0
	v_exp_f32_e32 v86, v0
	s_nop 0
	v_pk_mul_f32 v[12:13], v[48:49], v[86:87] op_sel_hi:[1,0]
	v_mul_f32_e32 v48, 0xbe38aa3b, v71
	v_fmamk_f32 v49, v82, 0x3e38aa3b, v48
	v_pk_mul_f32 v[14:15], v[50:51], v[86:87] op_sel_hi:[1,0]
	v_pk_mul_f32 v[0:1], v[60:61], v[86:87] op_sel_hi:[1,0]
	v_exp_f32_e32 v61, v49
	v_fmamk_f32 v50, v83, 0x3e38aa3b, v48
	v_pk_mul_f32 v[2:3], v[62:63], v[86:87] op_sel_hi:[1,0]
	v_exp_f32_e32 v63, v50
	v_fmamk_f32 v50, v84, 0x3e38aa3b, v48
	v_exp_f32_e32 v71, v50
	v_fmamk_f32 v50, v85, 0x3e38aa3b, v48
	v_exp_f32_e32 v73, v50
	v_fmamk_f32 v28, v28, 0x3e38aa3b, v48
	v_add_f32_e32 v49, 0, v61
	v_exp_f32_e32 v82, v28
	v_fmamk_f32 v29, v29, 0x3e38aa3b, v48
	v_add_f32_e32 v49, v63, v49
	v_exp_f32_e32 v83, v29
	v_fmamk_f32 v29, v30, 0x3e38aa3b, v48
	v_add_f32_e32 v49, v71, v49
	v_exp_f32_e32 v84, v29
	v_fmamk_f32 v29, v31, 0x3e38aa3b, v48
	v_add_f32_e32 v49, v73, v49
	v_exp_f32_e32 v85, v29
	v_fmamk_f32 v29, v74, 0x3e38aa3b, v48
	v_pk_mul_f32 v[8:9], v[52:53], v[86:87] op_sel_hi:[1,0]
	v_add_f32_e32 v28, v82, v49
	v_exp_f32_e32 v53, v29
	v_fmamk_f32 v29, v75, 0x3e38aa3b, v48
	v_pk_mul_f32 v[10:11], v[54:55], v[86:87] op_sel_hi:[1,0]
	v_add_f32_e32 v28, v83, v28
	v_exp_f32_e32 v54, v29
	v_fmamk_f32 v29, v76, 0x3e38aa3b, v48
	v_add_f32_e32 v28, v84, v28
	v_exp_f32_e32 v55, v29
	v_fmamk_f32 v29, v77, 0x3e38aa3b, v48
	v_pk_mul_f32 v[4:5], v[56:57], v[86:87] op_sel_hi:[1,0]
	v_add_f32_e32 v28, v85, v28
	v_exp_f32_e32 v56, v29
	v_fmamk_f32 v29, v78, 0x3e38aa3b, v48
	v_add_f32_e32 v28, v53, v28
	v_exp_f32_e32 v57, v29
	v_fmamk_f32 v29, v79, 0x3e38aa3b, v48
	v_pk_mul_f32 v[6:7], v[58:59], v[86:87] op_sel_hi:[1,0]
	v_add_f32_e32 v28, v54, v28
	v_exp_f32_e32 v58, v29
	v_fmamk_f32 v29, v80, 0x3e38aa3b, v48
	v_add_f32_e32 v28, v55, v28
	v_exp_f32_e32 v59, v29
	v_fmac_f32_e32 v48, 0x3e38aa3b, v81
	v_add_f32_e32 v28, v56, v28
	v_exp_f32_e32 v60, v48
	v_add_f32_e32 v28, v57, v28
	v_add_f32_e32 v28, v58, v28
	v_add_f32_e32 v28, v59, v28
	v_add_f32_e32 v52, v60, v28
	v_max3_f32 v28, v20, s38, v21
	v_max3_f32 v28, v28, v22, v23
	v_max3_f32 v28, v28, v16, v17
	v_max3_f32 v28, v28, v18, v19
	v_max3_f32 v28, v28, v24, v25
	v_max3_f32 v28, v28, v26, v27
	v_max3_f32 v28, v28, v64, v65
	v_max3_f32 v28, v28, v66, v67
	ds_bpermute_b32 v29, v145, v28
	v_fmac_f32_e32 v52, v97, v86
	s_waitcnt lgkmcnt(0)
	v_max_f32_e32 v29, v29, v29
	v_max_f32_e32 v28, v28, v29
	ds_bpermute_b32 v29, v99, v28
	s_waitcnt lgkmcnt(0)
	v_max3_f32 v74, v146, v28, v29
	v_sub_f32_e32 v28, v146, v74
	v_mul_f32_e32 v28, 0x3e38aa3b, v28
	v_exp_f32_e32 v62, v28
	s_nop 0
	v_pk_mul_f32 v[48:49], v[32:33], v[62:63] op_sel_hi:[1,0]
	v_pk_mul_f32 v[32:33], v[40:41], v[62:63] op_sel_hi:[1,0]
	v_mul_f32_e32 v40, 0xbe38aa3b, v74
	v_fmamk_f32 v20, v20, 0x3e38aa3b, v40
	v_pk_mul_f32 v[28:29], v[44:45], v[62:63] op_sel_hi:[1,0]
	v_exp_f32_e32 v44, v20
	v_fmamk_f32 v21, v21, 0x3e38aa3b, v40
	v_exp_f32_e32 v21, v21
	v_fmamk_f32 v22, v22, 0x3e38aa3b, v40
	v_exp_f32_e32 v45, v22
	v_fmamk_f32 v22, v23, 0x3e38aa3b, v40
	v_exp_f32_e32 v74, v22
	v_fmamk_f32 v16, v16, 0x3e38aa3b, v40
	v_pk_mul_f32 v[30:31], v[46:47], v[62:63] op_sel_hi:[1,0]
	v_add_f32_e32 v20, 0, v44
	v_exp_f32_e32 v46, v16
	v_fmamk_f32 v17, v17, 0x3e38aa3b, v40
	v_add_f32_e32 v20, v21, v20
	v_exp_f32_e32 v75, v17
	v_fmamk_f32 v17, v18, 0x3e38aa3b, v40
	v_add_f32_e32 v20, v45, v20
	v_exp_f32_e32 v47, v17
	v_fmamk_f32 v17, v19, 0x3e38aa3b, v40
	v_add_f32_e32 v20, v74, v20
	v_exp_f32_e32 v76, v17
	v_fmamk_f32 v17, v24, 0x3e38aa3b, v40
	v_add_f32_e32 v16, v46, v20
	v_exp_f32_e32 v77, v17
	v_fmamk_f32 v17, v25, 0x3e38aa3b, v40
	v_add_f32_e32 v16, v75, v16
	v_exp_f32_e32 v78, v17
	v_fmamk_f32 v17, v26, 0x3e38aa3b, v40
	v_add_f32_e32 v16, v47, v16
	v_exp_f32_e32 v79, v17
	v_fmamk_f32 v17, v27, 0x3e38aa3b, v40
	v_add_f32_e32 v16, v76, v16
	v_exp_f32_e32 v80, v17
	v_fmamk_f32 v17, v64, 0x3e38aa3b, v40
	ds_read2_b64 v[22:25], v72 offset0:128 offset1:132
	v_add_f32_e32 v16, v77, v16
	v_exp_f32_e32 v64, v17
	v_fmamk_f32 v17, v65, 0x3e38aa3b, v40
	v_add_f32_e32 v16, v78, v16
	v_exp_f32_e32 v65, v17
	v_fmamk_f32 v17, v66, 0x3e38aa3b, v40
	v_add_f32_e32 v16, v79, v16
	v_exp_f32_e32 v66, v17
	v_fmac_f32_e32 v40, 0x3e38aa3b, v67
	v_add_f32_e32 v16, v80, v16
	v_exp_f32_e32 v67, v40
	v_add_f32_e32 v16, v64, v16
	v_add_f32_e32 v16, v65, v16
	v_add_f32_e32 v16, v66, v16
	v_add_f32_e32 v20, v67, v16
	v_cvt_pk_bf16_f32 v19, v84, v85
	v_cvt_pk_bf16_f32 v18, v82, v83
	v_cvt_pk_bf16_f32 v17, v71, v73
	v_cvt_pk_bf16_f32 v16, v61, v63
	v_pk_mul_f32 v[50:51], v[34:35], v[62:63] op_sel_hi:[1,0]
	v_pk_mul_f32 v[34:35], v[42:43], v[62:63] op_sel_hi:[1,0]
	s_waitcnt lgkmcnt(0)
	v_mfma_f32_16x16x32_bf16 v[40:43], v[22:25], v[16:19], v[12:15]
	v_mul_f32_e64 v38, v38, v62
	v_mul_f32_e64 v39, v39, v62
	v_pk_mul_f32 v[36:37], v[36:37], v[62:63] op_sel_hi:[1,0]
	v_cvt_pk_bf16_f32 v47, v47, v76
	ds_read2_b64 v[12:15], v70 offset0:160 offset1:164
	v_cvt_pk_bf16_f32 v46, v46, v75
	v_cvt_pk_bf16_f32 v45, v45, v74
	v_cvt_pk_bf16_f32 v44, v44, v21
	ds_bpermute_b32 v21, v145, v52
	v_fmac_f32_e32 v20, v96, v62
	v_mfma_f32_16x16x32_bf16 v[22:25], v[22:25], v[44:47], v[48:51]
	s_waitcnt lgkmcnt(0)
	v_add_f32_e32 v21, v52, v21
	v_mfma_f32_16x16x32_bf16 v[48:51], v[12:15], v[16:19], v[8:11]
	v_mfma_f32_16x16x32_bf16 v[36:39], v[12:15], v[44:47], v[36:39]
	ds_read2_b64 v[12:15], v69 offset0:192 offset1:196
	s_waitcnt lgkmcnt(0)
	v_mfma_f32_16x16x32_bf16 v[8:11], v[12:15], v[16:19], v[4:7]
	s_nop 2
	ds_read2_b64 v[4:7], v68 offset0:224 offset1:228
	s_waitcnt lgkmcnt(0)
	v_mfma_f32_16x16x32_bf16 v[16:19], v[4:7], v[16:19], v[0:3]
	s_nop 2
	ds_read2_b64 v[0:3], v72 offset0:136 offset1:140
	v_mfma_f32_16x16x32_bf16 v[26:29], v[4:7], v[44:47], v[28:31]
	ds_read2_b64 v[4:7], v70 offset0:168 offset1:172
	v_mfma_f32_16x16x32_bf16 v[12:15], v[12:15], v[44:47], v[32:35]
	s_nop 0
	v_cvt_pk_bf16_f32 v31, v55, v56
	v_cvt_pk_bf16_f32 v30, v53, v54
	v_cvt_pk_bf16_f32 v47, v66, v67
	v_cvt_pk_bf16_f32 v33, v59, v60
	v_cvt_pk_bf16_f32 v32, v57, v58
	v_cvt_pk_bf16_f32 v46, v64, v65
	v_cvt_pk_bf16_f32 v45, v79, v80
	v_cvt_pk_bf16_f32 v44, v77, v78
	s_waitcnt lgkmcnt(1)
	v_mfma_f32_16x16x32_bf16 v[40:43], v[0:3], v[30:33], v[40:43]
	v_mfma_f32_16x16x32_bf16 v[0:3], v[0:3], v[44:47], v[22:25]
	s_waitcnt lgkmcnt(0)
	v_mfma_f32_16x16x32_bf16 v[22:25], v[4:7], v[30:33], v[48:51]
	v_mfma_f32_16x16x32_bf16 v[4:7], v[4:7], v[44:47], v[36:39]
	s_nop 2
	ds_read2_b64 v[34:37], v69 offset0:200 offset1:204
	s_waitcnt lgkmcnt(0)
	v_mfma_f32_16x16x32_bf16 v[48:51], v[34:37], v[30:33], v[8:11]
	s_nop 2
	ds_read2_b64 v[8:11], v68 offset0:232 offset1:236
	s_waitcnt lgkmcnt(0)
	v_mfma_f32_16x16x32_bf16 v[16:19], v[8:11], v[30:33], v[16:19]
	v_mov_b32_e32 v32, v41
	v_mov_b32_e32 v33, v42
	v_mfma_f32_16x16x32_bf16 v[8:11], v[8:11], v[44:47], v[26:29]
	s_nop 2
	ds_bpermute_b32 v28, v99, v21
	v_lshl_add_u64 v[26:27], v[92:93], 0, v[94:95]
	v_lshl_add_u64 v[30:31], v[26:27], 0, v[90:91]
	v_mfma_f32_16x16x32_bf16 v[12:15], v[34:37], v[44:47], v[12:15]
	s_waitcnt lgkmcnt(0)
	v_add_f32_e32 v21, v21, v28
	v_rcp_f32_e32 v28, v21
	s_nop 0
	v_mul_f32_e32 v21, v40, v28
	v_pk_mul_f32 v[32:33], v[32:33], v[28:29] op_sel_hi:[1,0]
	v_cvt_pk_bf16_f32 v21, v21, s0
	v_cvt_pk_bf16_f32 v29, v32, v33
	v_perm_b32 v32, v29, v21, s39
	v_mul_f32_e32 v21, v43, v28
	v_cvt_pk_bf16_f32 v21, v21, s0
	v_alignbit_b32 v33, v21, v29, 16
	v_mul_f32_e32 v21, v22, v28
	v_mov_b32_e32 v22, v23
	v_mov_b32_e32 v23, v24
	v_pk_mul_f32 v[22:23], v[22:23], v[28:29] op_sel_hi:[1,0]
	v_cvt_pk_bf16_f32 v21, v21, s0
	v_cvt_pk_bf16_f32 v23, v22, v23
	v_perm_b32 v22, v23, v21, s39
	v_mul_f32_e32 v21, v25, v28
	v_cvt_pk_bf16_f32 v21, v21, s0
	v_alignbit_b32 v23, v21, v23, 16
	global_store_dwordx2 v[30:31], v[22:23], off offset:32
	v_mov_b32_e32 v22, v49
	v_mov_b32_e32 v23, v50
	v_mul_f32_e32 v21, v48, v28
	v_pk_mul_f32 v[22:23], v[22:23], v[28:29] op_sel_hi:[1,0]
	v_cvt_pk_bf16_f32 v21, v21, s0
	v_cvt_pk_bf16_f32 v23, v22, v23
	v_perm_b32 v22, v23, v21, s39
	v_mul_f32_e32 v21, v51, v28
	v_cvt_pk_bf16_f32 v21, v21, s0
	v_mul_f32_e32 v16, v16, v28
	v_alignbit_b32 v23, v21, v23, 16
	v_cvt_pk_bf16_f32 v21, v16, s0
	v_mov_b32_e32 v16, v17
	v_mov_b32_e32 v17, v18
	v_pk_mul_f32 v[16:17], v[16:17], v[28:29] op_sel_hi:[1,0]
	v_mul_f32_e32 v18, v19, v28
	v_cvt_pk_bf16_f32 v17, v16, v17
	v_cvt_pk_bf16_f32 v18, v18, s0
	v_perm_b32 v16, v17, v21, s39
	v_alignbit_b32 v17, v18, v17, 16
	global_store_dwordx2 v[30:31], v[16:17], off offset:96
	ds_bpermute_b32 v16, v145, v20
	v_lshl_add_u64 v[18:19], v[26:27], 0, v[88:89]
	global_store_dwordx2 v[30:31], v[32:33], off
	global_store_dwordx2 v[30:31], v[22:23], off offset:64
	s_waitcnt lgkmcnt(0)
	v_add_f32_e32 v16, v20, v16
	ds_bpermute_b32 v17, v99, v16
	s_waitcnt lgkmcnt(0)
	v_add_f32_e32 v16, v16, v17
	v_rcp_f32_e32 v16, v16
	s_nop 0
	v_mul_f32_e32 v0, v0, v16
	v_cvt_pk_bf16_f32 v17, v0, s0
	v_mov_b32_e32 v0, v1
	v_mov_b32_e32 v1, v2
	v_pk_mul_f32 v[0:1], v[0:1], v[16:17] op_sel_hi:[1,0]
	v_mul_f32_e32 v2, v3, v16
	v_cvt_pk_bf16_f32 v1, v0, v1
	v_cvt_pk_bf16_f32 v2, v2, s0
	v_perm_b32 v0, v1, v17, s39
	v_alignbit_b32 v1, v2, v1, 16
	global_store_dwordx2 v[18:19], v[0:1], off
	v_mul_f32_e32 v0, v4, v16
	v_cvt_pk_bf16_f32 v2, v0, s0
	v_mov_b32_e32 v0, v5
	v_mov_b32_e32 v1, v6
	v_pk_mul_f32 v[0:1], v[0:1], v[16:17] op_sel_hi:[1,0]
	s_nop 0
	v_cvt_pk_bf16_f32 v1, v0, v1
	v_perm_b32 v0, v1, v2, s39
	v_mul_f32_e32 v2, v7, v16
	v_cvt_pk_bf16_f32 v2, v2, s0
	v_alignbit_b32 v1, v2, v1, 16
	global_store_dwordx2 v[18:19], v[0:1], off offset:32
	v_mul_f32_e32 v0, v12, v16
	v_cvt_pk_bf16_f32 v2, v0, s0
	v_mov_b32_e32 v0, v13
	v_mov_b32_e32 v1, v14
	v_pk_mul_f32 v[0:1], v[0:1], v[16:17] op_sel_hi:[1,0]
	s_nop 0
	v_cvt_pk_bf16_f32 v1, v0, v1
	v_perm_b32 v0, v1, v2, s39
	v_mul_f32_e32 v2, v15, v16
	v_cvt_pk_bf16_f32 v2, v2, s0
	v_alignbit_b32 v1, v2, v1, 16
	global_store_dwordx2 v[18:19], v[0:1], off offset:64
	v_mul_f32_e32 v0, v8, v16
	v_cvt_pk_bf16_f32 v2, v0, s0
	v_mov_b32_e32 v0, v9
	v_mov_b32_e32 v1, v10
	v_pk_mul_f32 v[0:1], v[0:1], v[16:17] op_sel_hi:[1,0]
	s_nop 0
	v_cvt_pk_bf16_f32 v1, v0, v1
	v_perm_b32 v0, v1, v2, s39
	v_mul_f32_e32 v2, v11, v16
	v_cvt_pk_bf16_f32 v2, v2, s0
	v_alignbit_b32 v1, v2, v1, 16
	global_store_dwordx2 v[18:19], v[0:1], off offset:96

.LBB0_467:
	v_add_u32_e32 v101, v98, v95
	s_barrier
	s_waitcnt vmcnt(3)
	ds_write_b128 v102, v[16:19]
	s_waitcnt vmcnt(2)
	ds_write_b128 v102, v[20:23] offset:9216
	s_waitcnt vmcnt(1)
	ds_write_b128 v100, v[24:27]
	s_waitcnt vmcnt(0)
	ds_write_b128 v100, v[28:31] offset:9216
	s_waitcnt lgkmcnt(0)
	s_barrier
	ds_read_b128 v[84:87], v101 offset:6912
	ds_read_b128 v[64:67], v101
	s_waitcnt lgkmcnt(1)
	v_mfma_f32_16x16x32_bf16 v[116:119], v[84:87], v[8:11], 0
	ds_read_b128 v[72:75], v101 offset:2304
	ds_read_b128 v[80:83], v101 offset:4608
	v_mov_b32_e32 v128, v146
	v_mfma_f32_16x16x32_bf16 v[120:123], v[84:87], v[12:15], 0
	ds_read_b128 v[84:87], v101 offset:64
	v_mov_b32_e32 v130, v103
	v_lshl_add_u64 v[16:17], v[106:107], 0, v[148:149]
	s_waitcnt lgkmcnt(3)
	v_mfma_f32_16x16x32_bf16 v[68:71], v[64:67], v[8:11], 0
	v_lshl_add_u64 v[20:21], v[110:111], 0, v[148:149]
	v_lshl_add_u64 v[24:25], v[104:105], 0, v[148:149]
	v_lshl_add_u64 v[28:29], v[108:109], 0, v[148:149]
	v_mfma_f32_16x16x32_bf16 v[64:67], v[64:67], v[12:15], 0
	global_load_dwordx4 v[16:19], v[16:17], off
	s_add_i32 s2, s2, -1
	global_load_dwordx4 v[20:23], v[20:21], off
	s_waitcnt lgkmcnt(0)
	v_mfma_f32_16x16x32_bf16 v[124:127], v[84:87], v[0:3], v[68:71]
	global_load_dwordx4 v[24:27], v[24:25], off
	v_lshl_add_u64 v[104:105], v[104:105], 0, s[72:73]
	global_load_dwordx4 v[28:31], v[28:29], off
	v_mfma_f32_16x16x32_bf16 v[84:87], v[84:87], v[4:7], v[64:67]
	v_lshl_add_u64 v[106:107], v[106:107], 0, s[72:73]
	v_lshl_add_u64 v[108:109], v[108:109], 0, s[52:53]
	v_lshl_add_u64 v[110:111], v[110:111], 0, s[52:53]
	ds_read_b128 v[64:67], v101 offset:2368
	v_mfma_f32_16x16x32_bf16 v[76:79], v[72:75], v[8:11], 0
	s_cmp_lg_u32 s2, 0
	v_mfma_f32_16x16x32_bf16 v[72:75], v[72:75], v[12:15], 0
	s_waitcnt lgkmcnt(0)
	v_mfma_f32_16x16x32_bf16 v[140:143], v[64:67], v[0:3], v[76:79]
	v_mfma_f32_16x16x32_bf16 v[72:75], v[64:67], v[4:7], v[72:75]
	ds_read_b128 v[64:67], v101 offset:4672
	v_mfma_f32_16x16x32_bf16 v[112:115], v[80:83], v[8:11], 0
	v_mfma_f32_16x16x32_bf16 v[80:83], v[80:83], v[12:15], 0
	s_waitcnt lgkmcnt(0)
	v_mfma_f32_16x16x32_bf16 v[150:153], v[64:67], v[0:3], v[112:115]
	v_mfma_f32_16x16x32_bf16 v[76:79], v[64:67], v[4:7], v[80:83]
	ds_read_b128 v[64:67], v101 offset:6976
	s_waitcnt lgkmcnt(0)
	v_mfma_f32_16x16x32_bf16 v[154:157], v[64:67], v[0:3], v[116:119]
	v_mfma_f32_16x16x32_bf16 v[80:83], v[64:67], v[4:7], v[120:123]
	v_max3_f32 v64, v124, s38, v125
	v_max3_f32 v64, v64, v126, v127
	v_max3_f32 v64, v64, v140, v141
	v_max3_f32 v64, v64, v142, v143
	v_max3_f32 v64, v64, v150, v151
	v_max3_f32 v64, v64, v152, v153
	s_nop 0
	v_max3_f32 v64, v64, v154, v155
	v_max3_f32 v64, v64, v156, v157
	ds_bpermute_b32 v65, v145, v64
	s_waitcnt lgkmcnt(0)
	v_max_f32_e32 v65, v65, v65
	v_max_f32_e32 v64, v64, v65
	ds_bpermute_b32 v65, v99, v64
	s_waitcnt lgkmcnt(0)
	v_max3_f32 v146, v128, v64, v65
	v_sub_f32_e32 v64, v128, v146
	v_mul_f32_e32 v64, 0x3e38aa3b, v64
	v_exp_f32_e32 v144, v64
	s_nop 0
	v_pk_mul_f32 v[64:65], v[52:53], v[144:145] op_sel_hi:[1,0]
	v_pk_mul_f32 v[52:53], v[56:57], v[144:145] op_sel_hi:[1,0]
	v_mul_f32_e32 v56, 0xbe38aa3b, v146
	v_pk_fma_f32 v[244:245], v[124:125], s[100:101], v[56:57] op_sel_hi:[1,0,0]
	v_exp_f32_e32 v129, v244
	v_exp_f32_e32 v131, v245
	v_pk_fma_f32 v[246:247], v[126:127], s[100:101], v[56:57] op_sel_hi:[1,0,0]
	v_exp_f32_e32 v133, v246
	v_exp_f32_e32 v135, v247
	v_pk_fma_f32 v[248:249], v[140:141], s[100:101], v[56:57] op_sel_hi:[1,0,0]
	v_exp_f32_e32 v137, v248
	v_exp_f32_e32 v139, v249
	v_pk_fma_f32 v[250:251], v[142:143], s[100:101], v[56:57] op_sel_hi:[1,0,0]
	v_exp_f32_e32 v141, v250
	v_exp_f32_e32 v143, v251
	v_pk_fma_f32 v[244:245], v[150:151], s[100:101], v[56:57] op_sel_hi:[1,0,0]
	v_exp_f32_e32 v113, v244
	v_exp_f32_e32 v115, v245
	v_pk_fma_f32 v[246:247], v[152:153], s[100:101], v[56:57] op_sel_hi:[1,0,0]
	v_exp_f32_e32 v117, v246
	v_exp_f32_e32 v119, v247
	v_pk_fma_f32 v[248:249], v[154:155], s[100:101], v[56:57] op_sel_hi:[1,0,0]
	v_exp_f32_e32 v121, v248
	v_exp_f32_e32 v123, v249
	v_fmamk_f32 v57, v156, 0x3e38aa3b, v56
	v_fmac_f32_e32 v56, 0x3e38aa3b, v157
	v_exp_f32_e32 v127, v56
	v_max3_f32 v56, v84, s38, v85
	v_max3_f32 v56, v56, v86, v87
	v_max3_f32 v56, v56, v72, v73
	v_max3_f32 v56, v56, v74, v75
	v_max3_f32 v56, v56, v76, v77
	v_max3_f32 v56, v56, v78, v79
	v_max3_f32 v56, v56, v80, v81
	v_max3_f32 v56, v56, v82, v83
	v_exp_f32_e32 v125, v57
	ds_bpermute_b32 v57, v145, v56
	v_pk_mul_f32 v[66:67], v[54:55], v[144:145] op_sel_hi:[1,0]
	v_pk_mul_f32 v[54:55], v[58:59], v[144:145] op_sel_hi:[1,0]
	v_pk_mul_f32 v[70:71], v[50:51], v[144:145] op_sel_hi:[1,0]
	v_pk_mul_f32 v[68:69], v[48:49], v[144:145] op_sel_hi:[1,0]
	s_waitcnt lgkmcnt(0)
	v_max_f32_e32 v57, v57, v57
	v_max_f32_e32 v56, v56, v57
	ds_bpermute_b32 v57, v99, v56
	v_pk_mul_f32 v[50:51], v[62:63], v[144:145] op_sel_hi:[1,0]
	v_pk_mul_f32 v[48:49], v[60:61], v[144:145] op_sel_hi:[1,0]
	s_waitcnt lgkmcnt(0)
	v_max3_f32 v103, v130, v56, v57
	v_sub_f32_e32 v56, v130, v103
	v_mul_f32_e32 v56, 0x3e38aa3b, v56
	v_exp_f32_e32 v150, v56
	s_nop 0
	v_pk_mul_f32 v[58:59], v[38:39], v[150:151] op_sel_hi:[1,0]
	v_pk_mul_f32 v[38:39], v[42:43], v[150:151] op_sel_hi:[1,0]
	v_mul_f32_e32 v42, 0xbe38aa3b, v103
	v_pk_mul_f32 v[56:57], v[36:37], v[150:151] op_sel_hi:[1,0]
	v_pk_mul_f32 v[36:37], v[40:41], v[150:151] op_sel_hi:[1,0]
	v_pk_fma_f32 v[250:251], v[84:85], s[100:101], v[42:43] op_sel_hi:[1,0,0]
	v_exp_f32_e32 v128, v250
	v_exp_f32_e32 v130, v251
	v_pk_fma_f32 v[244:245], v[86:87], s[100:101], v[42:43] op_sel_hi:[1,0,0]
	v_exp_f32_e32 v132, v244
	v_exp_f32_e32 v134, v245
	v_pk_fma_f32 v[246:247], v[72:73], s[100:101], v[42:43] op_sel_hi:[1,0,0]
	v_exp_f32_e32 v136, v246
	v_exp_f32_e32 v138, v247
	v_pk_add_f32 v[40:41], v[128:129], 0 op_sel_hi:[1,0]
	v_pk_fma_f32 v[248:249], v[74:75], s[100:101], v[42:43] op_sel_hi:[1,0,0]
	v_pk_add_f32 v[40:41], v[130:131], v[40:41]
	v_exp_f32_e32 v140, v248
	v_pk_add_f32 v[40:41], v[132:133], v[40:41]
	v_pk_add_f32 v[40:41], v[134:135], v[40:41]
	v_exp_f32_e32 v142, v249
	v_pk_fma_f32 v[250:251], v[76:77], s[100:101], v[42:43] op_sel_hi:[1,0,0]
	v_pk_add_f32 v[40:41], v[136:137], v[40:41]
	v_exp_f32_e32 v112, v250
	v_pk_add_f32 v[40:41], v[138:139], v[40:41]
	v_exp_f32_e32 v114, v251
	v_pk_fma_f32 v[244:245], v[78:79], s[100:101], v[42:43] op_sel_hi:[1,0,0]
	v_exp_f32_e32 v116, v244
	v_pk_add_f32 v[40:41], v[140:141], v[40:41]
	v_add_u32_e32 v73, v94, v95
	v_exp_f32_e32 v118, v245
	v_pk_fma_f32 v[246:247], v[80:81], s[100:101], v[42:43] op_sel_hi:[1,0,0]
	v_pk_add_f32 v[40:41], v[142:143], v[40:41]
	v_add_u32_e32 v72, 0x2000, v73
	v_pk_mul_f32 v[62:63], v[34:35], v[150:151] op_sel_hi:[1,0]
	v_pk_mul_f32 v[60:61], v[32:33], v[150:151] op_sel_hi:[1,0]
	v_pk_mul_f32 v[34:35], v[46:47], v[150:151] op_sel_hi:[1,0]
	v_pk_mul_f32 v[32:33], v[44:45], v[150:151] op_sel_hi:[1,0]
	v_exp_f32_e32 v120, v246
	v_pk_add_f32 v[40:41], v[112:113], v[40:41]
	ds_read2_b64 v[44:47], v72 offset0:128 offset1:132
	v_exp_f32_e32 v122, v247
	v_fmamk_f32 v43, v82, 0x3e38aa3b, v42
	v_pk_add_f32 v[40:41], v[114:115], v[40:41]
	v_exp_f32_e32 v124, v43
	v_fmac_f32_e32 v42, 0x3e38aa3b, v83
	v_pk_add_f32 v[40:41], v[116:117], v[40:41]
	v_exp_f32_e32 v126, v42
	v_pk_add_f32 v[40:41], v[118:119], v[40:41]
	v_mov_b32_e32 v151, v144
	v_pk_add_f32 v[40:41], v[120:121], v[40:41]
	v_cvt_pk_bf16_f32 v43, v141, v143
	v_pk_add_f32 v[40:41], v[122:123], v[40:41]
	v_cvt_pk_bf16_f32 v42, v137, v139
	v_pk_add_f32 v[40:41], v[124:125], v[40:41]
	v_cvt_pk_bf16_f32 v81, v140, v142
	v_pk_add_f32 v[40:41], v[126:127], v[40:41]
	v_cvt_pk_bf16_f32 v80, v136, v138
	v_pk_fma_f32 v[96:97], v[96:97], v[150:151], v[40:41]
	v_cvt_pk_bf16_f32 v41, v133, v135
	v_cvt_pk_bf16_f32 v40, v129, v131
	v_cvt_pk_bf16_f32 v79, v132, v134
	v_cvt_pk_bf16_f32 v78, v128, v130
	s_waitcnt lgkmcnt(0)
	v_mfma_f32_16x16x32_bf16 v[74:77], v[44:47], v[40:43], v[68:71]
	v_cvt_pk_bf16_f32 v135, v125, v127
	v_cvt_pk_bf16_f32 v134, v121, v123
	v_cvt_pk_bf16_f32 v133, v117, v119
	v_add_u32_e32 v70, 0x2800, v73
	v_mfma_f32_16x16x32_bf16 v[44:47], v[44:47], v[78:81], v[60:63]
	v_add_u32_e32 v69, 0x3000, v73
	v_add_u32_e32 v68, 0x3800, v73
	v_cvt_pk_bf16_f32 v132, v113, v115
	ds_read2_b64 v[60:63], v70 offset0:160 offset1:164
	s_waitcnt lgkmcnt(0)
	v_mfma_f32_16x16x32_bf16 v[64:67], v[60:63], v[40:43], v[64:67]
	v_mfma_f32_16x16x32_bf16 v[56:59], v[60:63], v[78:81], v[56:59]
	ds_read2_b64 v[60:63], v69 offset0:192 offset1:196
	s_waitcnt lgkmcnt(0)
	v_mfma_f32_16x16x32_bf16 v[82:85], v[60:63], v[40:43], v[52:55]
	v_mfma_f32_16x16x32_bf16 v[60:63], v[60:63], v[78:81], v[36:39]
	s_nop 2
	ds_read2_b64 v[36:39], v68 offset0:224 offset1:228
	s_waitcnt lgkmcnt(0)
	v_mfma_f32_16x16x32_bf16 v[78:81], v[36:39], v[78:81], v[32:35]
	s_nop 2
	ds_read2_b64 v[32:35], v72 offset0:136 offset1:140
	v_mfma_f32_16x16x32_bf16 v[128:131], v[36:39], v[40:43], v[48:51]
	ds_read2_b64 v[36:39], v70 offset0:168 offset1:172
	ds_read2_b64 v[40:43], v69 offset0:200 offset1:204
	s_waitcnt lgkmcnt(2)
	v_mfma_f32_16x16x32_bf16 v[48:51], v[32:35], v[132:135], v[74:77]
	s_nop 2
	v_cvt_pk_bf16_f32 v77, v124, v126
	v_cvt_pk_bf16_f32 v76, v120, v122
	v_cvt_pk_bf16_f32 v75, v116, v118
	v_cvt_pk_bf16_f32 v74, v112, v114
	s_waitcnt lgkmcnt(1)
	v_mfma_f32_16x16x32_bf16 v[52:55], v[36:39], v[132:135], v[64:67]
	v_mfma_f32_16x16x32_bf16 v[32:35], v[32:35], v[74:77], v[44:47]
	s_nop 2
	ds_read2_b64 v[44:47], v68 offset0:232 offset1:236
	v_mfma_f32_16x16x32_bf16 v[36:39], v[36:39], v[74:77], v[56:59]
	s_waitcnt lgkmcnt(1)
	v_mfma_f32_16x16x32_bf16 v[56:59], v[40:43], v[132:135], v[82:85]
	v_mfma_f32_16x16x32_bf16 v[40:43], v[40:43], v[74:77], v[60:63]
	s_waitcnt lgkmcnt(0)
	v_mfma_f32_16x16x32_bf16 v[60:63], v[44:47], v[132:135], v[128:131]
	v_mfma_f32_16x16x32_bf16 v[44:47], v[44:47], v[74:77], v[78:81]
	s_cbranch_scc1 .LBB0_467
	s_barrier
	s_waitcnt vmcnt(3)
	ds_write_b128 v102, v[16:19]
	s_waitcnt vmcnt(2)
	ds_write_b128 v102, v[20:23] offset:9216
	s_waitcnt vmcnt(1)
	ds_write_b128 v100, v[24:27]
	s_waitcnt vmcnt(0)
	ds_write_b128 v100, v[28:31] offset:9216
	s_waitcnt lgkmcnt(0)
	s_barrier
	ds_read_b128 v[16:19], v101
	ds_read_b128 v[24:27], v101 offset:2304
	ds_read_b128 v[64:67], v101 offset:4608
	ds_read_b128 v[78:81], v101 offset:6912
	s_waitcnt lgkmcnt(3)
	v_mfma_f32_16x16x32_bf16 v[20:23], v[16:19], v[8:11], 0
	v_mov_b32_e32 v95, v149
	v_mfma_f32_16x16x32_bf16 v[16:19], v[16:19], v[12:15], 0
	s_waitcnt lgkmcnt(2)
	v_mfma_f32_16x16x32_bf16 v[28:31], v[24:27], v[8:11], 0
	v_mfma_f32_16x16x32_bf16 v[24:27], v[24:27], v[12:15], 0
	s_waitcnt lgkmcnt(1)
	v_mfma_f32_16x16x32_bf16 v[74:77], v[64:67], v[8:11], 0
	v_mfma_f32_16x16x32_bf16 v[64:67], v[64:67], v[12:15], 0
	s_waitcnt lgkmcnt(0)
	v_mfma_f32_16x16x32_bf16 v[8:11], v[78:81], v[8:11], 0
	v_mfma_f32_16x16x32_bf16 v[12:15], v[78:81], v[12:15], 0
	ds_read_b128 v[78:81], v101 offset:64
	s_waitcnt lgkmcnt(0)
	v_mfma_f32_16x16x32_bf16 v[82:85], v[78:81], v[0:3], v[20:23]
	v_mfma_f32_16x16x32_bf16 v[20:23], v[78:81], v[4:7], v[16:19]
	s_nop 2
	ds_read_b128 v[16:19], v101 offset:2368
	s_waitcnt lgkmcnt(0)
	v_mfma_f32_16x16x32_bf16 v[28:31], v[16:19], v[0:3], v[28:31]
	v_mfma_f32_16x16x32_bf16 v[16:19], v[16:19], v[4:7], v[24:27]
	s_nop 2
	ds_read_b128 v[24:27], v101 offset:4672
	s_waitcnt lgkmcnt(0)
	v_mfma_f32_16x16x32_bf16 v[74:77], v[24:27], v[0:3], v[74:77]
	v_mfma_f32_16x16x32_bf16 v[24:27], v[24:27], v[4:7], v[64:67]
	s_nop 2
	ds_read_b128 v[64:67], v101 offset:6976
	s_waitcnt lgkmcnt(0)
	v_mfma_f32_16x16x32_bf16 v[78:81], v[64:67], v[0:3], v[8:11]
	v_max3_f32 v0, v82, s38, v83
	v_max3_f32 v0, v0, v84, v85
	v_max3_f32 v0, v0, v28, v29
	v_max3_f32 v0, v0, v30, v31
	v_max3_f32 v0, v0, v74, v75
	v_max3_f32 v0, v0, v76, v77
	s_nop 1
	v_max3_f32 v0, v0, v78, v79
	v_max3_f32 v0, v0, v80, v81
	ds_bpermute_b32 v1, v145, v0
	v_mfma_f32_16x16x32_bf16 v[64:67], v[64:67], v[4:7], v[12:15]
	s_waitcnt lgkmcnt(0)
	v_max_f32_e32 v1, v1, v1
	v_max_f32_e32 v0, v0, v1
	ds_bpermute_b32 v1, v99, v0
	s_waitcnt lgkmcnt(0)
	v_max3_f32 v71, v146, v0, v1
	v_sub_f32_e32 v0, v146, v71
	v_mul_f32_e32 v0, 0x3e38aa3b, v0
	v_exp_f32_e32 v86, v0
	s_nop 0
	v_pk_mul_f32 v[12:13], v[48:49], v[86:87] op_sel_hi:[1,0]
	v_mul_f32_e32 v48, 0xbe38aa3b, v71
	v_fmamk_f32 v49, v82, 0x3e38aa3b, v48
	v_pk_mul_f32 v[14:15], v[50:51], v[86:87] op_sel_hi:[1,0]
	v_pk_mul_f32 v[0:1], v[60:61], v[86:87] op_sel_hi:[1,0]
	v_exp_f32_e32 v61, v49
	v_fmamk_f32 v50, v83, 0x3e38aa3b, v48
	v_pk_mul_f32 v[2:3], v[62:63], v[86:87] op_sel_hi:[1,0]
	v_exp_f32_e32 v63, v50
	v_fmamk_f32 v50, v84, 0x3e38aa3b, v48
	v_exp_f32_e32 v71, v50
	v_fmamk_f32 v50, v85, 0x3e38aa3b, v48
	v_exp_f32_e32 v73, v50
	v_fmamk_f32 v28, v28, 0x3e38aa3b, v48
	v_add_f32_e32 v49, 0, v61
	v_exp_f32_e32 v82, v28
	v_fmamk_f32 v29, v29, 0x3e38aa3b, v48
	v_add_f32_e32 v49, v63, v49
	v_exp_f32_e32 v83, v29
	v_fmamk_f32 v29, v30, 0x3e38aa3b, v48
	v_add_f32_e32 v49, v71, v49
	v_exp_f32_e32 v84, v29
	v_fmamk_f32 v29, v31, 0x3e38aa3b, v48
	v_add_f32_e32 v49, v73, v49
	v_exp_f32_e32 v85, v29
	v_fmamk_f32 v29, v74, 0x3e38aa3b, v48
	v_pk_mul_f32 v[8:9], v[52:53], v[86:87] op_sel_hi:[1,0]
	v_add_f32_e32 v28, v82, v49
	v_exp_f32_e32 v53, v29
	v_fmamk_f32 v29, v75, 0x3e38aa3b, v48
	v_pk_mul_f32 v[10:11], v[54:55], v[86:87] op_sel_hi:[1,0]
	v_add_f32_e32 v28, v83, v28
	v_exp_f32_e32 v54, v29
	v_fmamk_f32 v29, v76, 0x3e38aa3b, v48
	v_add_f32_e32 v28, v84, v28
	v_exp_f32_e32 v55, v29
	v_fmamk_f32 v29, v77, 0x3e38aa3b, v48
	v_pk_mul_f32 v[4:5], v[56:57], v[86:87] op_sel_hi:[1,0]
	v_add_f32_e32 v28, v85, v28
	v_exp_f32_e32 v56, v29
	v_fmamk_f32 v29, v78, 0x3e38aa3b, v48
	v_add_f32_e32 v28, v53, v28
	v_exp_f32_e32 v57, v29
	v_fmamk_f32 v29, v79, 0x3e38aa3b, v48
	v_pk_mul_f32 v[6:7], v[58:59], v[86:87] op_sel_hi:[1,0]
	v_add_f32_e32 v28, v54, v28
	v_exp_f32_e32 v58, v29
	v_fmamk_f32 v29, v80, 0x3e38aa3b, v48
	v_add_f32_e32 v28, v55, v28
	v_exp_f32_e32 v59, v29
	v_fmac_f32_e32 v48, 0x3e38aa3b, v81
	v_add_f32_e32 v28, v56, v28
	v_exp_f32_e32 v60, v48
	v_add_f32_e32 v28, v57, v28
	v_add_f32_e32 v28, v58, v28
	v_add_f32_e32 v28, v59, v28
	v_add_f32_e32 v52, v60, v28
	v_max3_f32 v28, v20, s38, v21
	v_max3_f32 v28, v28, v22, v23
	v_max3_f32 v28, v28, v16, v17
	v_max3_f32 v28, v28, v18, v19
	v_max3_f32 v28, v28, v24, v25
	v_max3_f32 v28, v28, v26, v27
	v_max3_f32 v28, v28, v64, v65
	v_max3_f32 v28, v28, v66, v67
	ds_bpermute_b32 v29, v145, v28
	v_fmac_f32_e32 v52, v97, v86
	s_waitcnt lgkmcnt(0)
	v_max_f32_e32 v29, v29, v29
	v_max_f32_e32 v28, v28, v29
	ds_bpermute_b32 v29, v99, v28
	s_waitcnt lgkmcnt(0)
	v_max3_f32 v74, v103, v28, v29
	v_sub_f32_e32 v28, v103, v74
	v_mul_f32_e32 v28, 0x3e38aa3b, v28
	v_exp_f32_e32 v62, v28
	s_nop 0
	v_pk_mul_f32 v[48:49], v[32:33], v[62:63] op_sel_hi:[1,0]
	v_pk_mul_f32 v[32:33], v[40:41], v[62:63] op_sel_hi:[1,0]
	v_mul_f32_e32 v40, 0xbe38aa3b, v74
	v_fmamk_f32 v20, v20, 0x3e38aa3b, v40
	v_pk_mul_f32 v[28:29], v[44:45], v[62:63] op_sel_hi:[1,0]
	v_exp_f32_e32 v44, v20
	v_fmamk_f32 v21, v21, 0x3e38aa3b, v40
	v_exp_f32_e32 v21, v21
	v_fmamk_f32 v22, v22, 0x3e38aa3b, v40
	v_exp_f32_e32 v45, v22
	v_fmamk_f32 v22, v23, 0x3e38aa3b, v40
	v_exp_f32_e32 v74, v22
	v_fmamk_f32 v16, v16, 0x3e38aa3b, v40
	v_pk_mul_f32 v[30:31], v[46:47], v[62:63] op_sel_hi:[1,0]
	v_add_f32_e32 v20, 0, v44
	v_exp_f32_e32 v46, v16
	v_fmamk_f32 v17, v17, 0x3e38aa3b, v40
	v_add_f32_e32 v20, v21, v20
	v_exp_f32_e32 v75, v17
	v_fmamk_f32 v17, v18, 0x3e38aa3b, v40
	v_add_f32_e32 v20, v45, v20
	v_exp_f32_e32 v47, v17
	v_fmamk_f32 v17, v19, 0x3e38aa3b, v40
	v_add_f32_e32 v20, v74, v20
	v_exp_f32_e32 v76, v17
	v_fmamk_f32 v17, v24, 0x3e38aa3b, v40
	v_add_f32_e32 v16, v46, v20
	v_exp_f32_e32 v77, v17
	v_fmamk_f32 v17, v25, 0x3e38aa3b, v40
	v_add_f32_e32 v16, v75, v16
	v_exp_f32_e32 v78, v17
	v_fmamk_f32 v17, v26, 0x3e38aa3b, v40
	v_add_f32_e32 v16, v47, v16
	v_exp_f32_e32 v79, v17
	v_fmamk_f32 v17, v27, 0x3e38aa3b, v40
	v_add_f32_e32 v16, v76, v16
	v_exp_f32_e32 v80, v17
	v_fmamk_f32 v17, v64, 0x3e38aa3b, v40
	ds_read2_b64 v[22:25], v72 offset0:128 offset1:132
	v_add_f32_e32 v16, v77, v16
	v_exp_f32_e32 v64, v17
	v_fmamk_f32 v17, v65, 0x3e38aa3b, v40
	v_add_f32_e32 v16, v78, v16
	v_exp_f32_e32 v65, v17
	v_fmamk_f32 v17, v66, 0x3e38aa3b, v40
	v_add_f32_e32 v16, v79, v16
	v_exp_f32_e32 v66, v17
	v_fmac_f32_e32 v40, 0x3e38aa3b, v67
	v_add_f32_e32 v16, v80, v16
	v_exp_f32_e32 v67, v40
	v_add_f32_e32 v16, v64, v16
	v_add_f32_e32 v16, v65, v16
	v_add_f32_e32 v16, v66, v16
	v_add_f32_e32 v20, v67, v16
	v_cvt_pk_bf16_f32 v19, v84, v85
	v_cvt_pk_bf16_f32 v18, v82, v83
	v_cvt_pk_bf16_f32 v17, v71, v73
	v_cvt_pk_bf16_f32 v16, v61, v63
	v_pk_mul_f32 v[50:51], v[34:35], v[62:63] op_sel_hi:[1,0]
	v_pk_mul_f32 v[34:35], v[42:43], v[62:63] op_sel_hi:[1,0]
	s_waitcnt lgkmcnt(0)
	v_mfma_f32_16x16x32_bf16 v[40:43], v[22:25], v[16:19], v[12:15]
	v_mul_f32_e64 v38, v38, v62
	v_mul_f32_e64 v39, v39, v62
	v_pk_mul_f32 v[36:37], v[36:37], v[62:63] op_sel_hi:[1,0]
	v_cvt_pk_bf16_f32 v47, v47, v76
	ds_read2_b64 v[12:15], v70 offset0:160 offset1:164
	v_cvt_pk_bf16_f32 v46, v46, v75
	v_cvt_pk_bf16_f32 v45, v45, v74
	v_cvt_pk_bf16_f32 v44, v44, v21
	ds_bpermute_b32 v21, v145, v52
	v_fmac_f32_e32 v20, v96, v62
	v_mfma_f32_16x16x32_bf16 v[22:25], v[22:25], v[44:47], v[48:51]
	s_waitcnt lgkmcnt(0)
	v_add_f32_e32 v21, v52, v21
	v_mfma_f32_16x16x32_bf16 v[48:51], v[12:15], v[16:19], v[8:11]
	v_mfma_f32_16x16x32_bf16 v[36:39], v[12:15], v[44:47], v[36:39]
	ds_read2_b64 v[12:15], v69 offset0:192 offset1:196
	s_waitcnt lgkmcnt(0)
	v_mfma_f32_16x16x32_bf16 v[8:11], v[12:15], v[16:19], v[4:7]
	s_nop 2
	ds_read2_b64 v[4:7], v68 offset0:224 offset1:228
	s_waitcnt lgkmcnt(0)
	v_mfma_f32_16x16x32_bf16 v[16:19], v[4:7], v[16:19], v[0:3]
	s_nop 2
	ds_read2_b64 v[0:3], v72 offset0:136 offset1:140
	v_mfma_f32_16x16x32_bf16 v[26:29], v[4:7], v[44:47], v[28:31]
	ds_read2_b64 v[4:7], v70 offset0:168 offset1:172
	v_mfma_f32_16x16x32_bf16 v[12:15], v[12:15], v[44:47], v[32:35]
	s_nop 0
	v_cvt_pk_bf16_f32 v31, v55, v56
	v_cvt_pk_bf16_f32 v30, v53, v54
	v_cvt_pk_bf16_f32 v47, v66, v67
	v_cvt_pk_bf16_f32 v33, v59, v60
	v_cvt_pk_bf16_f32 v32, v57, v58
	v_cvt_pk_bf16_f32 v46, v64, v65
	v_cvt_pk_bf16_f32 v45, v79, v80
	v_cvt_pk_bf16_f32 v44, v77, v78
	s_waitcnt lgkmcnt(1)
	v_mfma_f32_16x16x32_bf16 v[40:43], v[0:3], v[30:33], v[40:43]
	v_mfma_f32_16x16x32_bf16 v[0:3], v[0:3], v[44:47], v[22:25]
	s_waitcnt lgkmcnt(0)
	v_mfma_f32_16x16x32_bf16 v[22:25], v[4:7], v[30:33], v[48:51]
	v_mfma_f32_16x16x32_bf16 v[4:7], v[4:7], v[44:47], v[36:39]
	s_nop 2
	ds_read2_b64 v[34:37], v69 offset0:200 offset1:204
	s_waitcnt lgkmcnt(0)
	v_mfma_f32_16x16x32_bf16 v[48:51], v[34:37], v[30:33], v[8:11]
	s_nop 2
	ds_read2_b64 v[8:11], v68 offset0:232 offset1:236
	s_waitcnt lgkmcnt(0)
	v_mfma_f32_16x16x32_bf16 v[16:19], v[8:11], v[30:33], v[16:19]
	v_mov_b32_e32 v32, v41
	v_mov_b32_e32 v33, v42
	v_mfma_f32_16x16x32_bf16 v[8:11], v[8:11], v[44:47], v[26:29]
	s_nop 2
	ds_bpermute_b32 v28, v99, v21
	v_lshl_add_u64 v[26:27], v[92:93], 0, v[94:95]
	v_lshl_add_u64 v[30:31], v[26:27], 0, v[90:91]
	v_mfma_f32_16x16x32_bf16 v[12:15], v[34:37], v[44:47], v[12:15]
	s_waitcnt lgkmcnt(0)
	v_add_f32_e32 v21, v21, v28
	v_rcp_f32_e32 v28, v21
	s_nop 0
	v_mul_f32_e32 v21, v40, v28
	v_pk_mul_f32 v[32:33], v[32:33], v[28:29] op_sel_hi:[1,0]
	v_cvt_pk_bf16_f32 v21, v21, s0
	v_cvt_pk_bf16_f32 v29, v32, v33
	v_perm_b32 v32, v29, v21, s39
	v_mul_f32_e32 v21, v43, v28
	v_cvt_pk_bf16_f32 v21, v21, s0
	v_alignbit_b32 v33, v21, v29, 16
	v_mul_f32_e32 v21, v22, v28
	v_mov_b32_e32 v22, v23
	v_mov_b32_e32 v23, v24
	v_pk_mul_f32 v[22:23], v[22:23], v[28:29] op_sel_hi:[1,0]
	v_cvt_pk_bf16_f32 v21, v21, s0
	v_cvt_pk_bf16_f32 v23, v22, v23
	v_perm_b32 v22, v23, v21, s39
	v_mul_f32_e32 v21, v25, v28
	v_cvt_pk_bf16_f32 v21, v21, s0
	v_alignbit_b32 v23, v21, v23, 16
	global_store_dwordx2 v[30:31], v[22:23], off offset:32
	v_mov_b32_e32 v22, v49
	v_mov_b32_e32 v23, v50
	v_mul_f32_e32 v21, v48, v28
	v_pk_mul_f32 v[22:23], v[22:23], v[28:29] op_sel_hi:[1,0]
	v_cvt_pk_bf16_f32 v21, v21, s0
	v_cvt_pk_bf16_f32 v23, v22, v23
	v_perm_b32 v22, v23, v21, s39
	v_mul_f32_e32 v21, v51, v28
	v_cvt_pk_bf16_f32 v21, v21, s0
	v_mul_f32_e32 v16, v16, v28
	v_alignbit_b32 v23, v21, v23, 16
	v_cvt_pk_bf16_f32 v21, v16, s0
	v_mov_b32_e32 v16, v17
	v_mov_b32_e32 v17, v18
	v_pk_mul_f32 v[16:17], v[16:17], v[28:29] op_sel_hi:[1,0]
	v_mul_f32_e32 v18, v19, v28
	v_cvt_pk_bf16_f32 v17, v16, v17
	v_cvt_pk_bf16_f32 v18, v18, s0
	v_perm_b32 v16, v17, v21, s39
	v_alignbit_b32 v17, v18, v17, 16
	global_store_dwordx2 v[30:31], v[16:17], off offset:96
	ds_bpermute_b32 v16, v145, v20
	v_lshl_add_u64 v[18:19], v[26:27], 0, v[88:89]
	global_store_dwordx2 v[30:31], v[32:33], off
	global_store_dwordx2 v[30:31], v[22:23], off offset:64
	s_waitcnt lgkmcnt(0)
	v_add_f32_e32 v16, v20, v16
	ds_bpermute_b32 v17, v99, v16
	s_waitcnt lgkmcnt(0)
	v_add_f32_e32 v16, v16, v17
	v_rcp_f32_e32 v16, v16
	s_nop 0
	v_mul_f32_e32 v0, v0, v16
	v_cvt_pk_bf16_f32 v17, v0, s0
	v_mov_b32_e32 v0, v1
	v_mov_b32_e32 v1, v2
	v_pk_mul_f32 v[0:1], v[0:1], v[16:17] op_sel_hi:[1,0]
	v_mul_f32_e32 v2, v3, v16
	v_cvt_pk_bf16_f32 v1, v0, v1
	v_cvt_pk_bf16_f32 v2, v2, s0
	v_perm_b32 v0, v1, v17, s39
	v_alignbit_b32 v1, v2, v1, 16
	global_store_dwordx2 v[18:19], v[0:1], off
	v_mul_f32_e32 v0, v4, v16
	v_cvt_pk_bf16_f32 v2, v0, s0
	v_mov_b32_e32 v0, v5
	v_mov_b32_e32 v1, v6
	v_pk_mul_f32 v[0:1], v[0:1], v[16:17] op_sel_hi:[1,0]
	s_nop 0
	v_cvt_pk_bf16_f32 v1, v0, v1
	v_perm_b32 v0, v1, v2, s39
	v_mul_f32_e32 v2, v7, v16
	v_cvt_pk_bf16_f32 v2, v2, s0
	v_alignbit_b32 v1, v2, v1, 16
	global_store_dwordx2 v[18:19], v[0:1], off offset:32
	v_mul_f32_e32 v0, v12, v16
	v_cvt_pk_bf16_f32 v2, v0, s0
	v_mov_b32_e32 v0, v13
	v_mov_b32_e32 v1, v14
	v_pk_mul_f32 v[0:1], v[0:1], v[16:17] op_sel_hi:[1,0]
	s_nop 0
	v_cvt_pk_bf16_f32 v1, v0, v1
	v_perm_b32 v0, v1, v2, s39
	v_mul_f32_e32 v2, v15, v16
	v_cvt_pk_bf16_f32 v2, v2, s0
	v_alignbit_b32 v1, v2, v1, 16
	global_store_dwordx2 v[18:19], v[0:1], off offset:64
	v_mul_f32_e32 v0, v8, v16
	v_cvt_pk_bf16_f32 v2, v0, s0
	v_mov_b32_e32 v0, v9
	v_mov_b32_e32 v1, v10
	v_pk_mul_f32 v[0:1], v[0:1], v[16:17] op_sel_hi:[1,0]
	s_nop 0
	v_cvt_pk_bf16_f32 v1, v0, v1
	v_perm_b32 v0, v1, v2, s39
	v_mul_f32_e32 v2, v11, v16
	v_cvt_pk_bf16_f32 v2, v2, s0
	v_alignbit_b32 v1, v2, v1, 16
	global_store_dwordx2 v[18:19], v[0:1], off offset:96

	.amdhsa_kernel _Z14fwd_megakernel6Params
		.amdhsa_group_segment_fixed_size 73728
		.amdhsa_private_segment_fixed_size 0
		.amdhsa_kernarg_size 552
		.amdhsa_user_sgpr_count 2
		.amdhsa_user_sgpr_dispatch_ptr 0
		.amdhsa_user_sgpr_queue_ptr 0
		.amdhsa_user_sgpr_kernarg_segment_ptr 1
		.amdhsa_user_sgpr_dispatch_id 0
		.amdhsa_user_sgpr_kernarg_preload_length 0
		.amdhsa_user_sgpr_kernarg_preload_offset 0
		.amdhsa_user_sgpr_private_segment_size 0
		.amdhsa_uses_dynamic_stack 0
		.amdhsa_enable_private_segment 0
		.amdhsa_system_sgpr_workgroup_id_x 1
		.amdhsa_system_sgpr_workgroup_id_y 0
		.amdhsa_system_sgpr_workgroup_id_z 0
		.amdhsa_system_sgpr_workgroup_info 0
		.amdhsa_system_vgpr_workitem_id 2
		.amdhsa_next_free_vgpr 256
		.amdhsa_next_free_sgpr 102
		.amdhsa_accum_offset 256
		.amdhsa_reserve_vcc 1
		.amdhsa_float_round_mode_32 0
		.amdhsa_float_round_mode_16_64 0
		.amdhsa_float_denorm_mode_32 3
		.amdhsa_float_denorm_mode_16_64 3
		.amdhsa_dx10_clamp 1
		.amdhsa_ieee_mode 1
		.amdhsa_fp16_overflow 0
		.amdhsa_tg_split 0
		.amdhsa_exception_fp_ieee_invalid_op 0
		.amdhsa_exception_fp_denorm_src 0
		.amdhsa_exception_fp_ieee_div_zero 0
		.amdhsa_exception_fp_ieee_overflow 0
		.amdhsa_exception_fp_ieee_underflow 0
		.amdhsa_exception_fp_ieee_inexact 0
		.amdhsa_exception_int_div_zero 0
	.end_amdhsa_kernel

amdhsa.kernels:
  - .agpr_count:     0
    .args:
      - .offset:         0
        .size:           296
        .value_kind:     by_value
      - .offset:         296
        .size:           4
        .value_kind:     hidden_block_count_x
      - .offset:         300
        .size:           4
        .value_kind:     hidden_block_count_y
      - .offset:         304
        .size:           4
        .value_kind:     hidden_block_count_z
      - .offset:         308
        .size:           2
        .value_kind:     hidden_group_size_x
      - .offset:         310
        .size:           2
        .value_kind:     hidden_group_size_y
      - .offset:         312
        .size:           2
        .value_kind:     hidden_group_size_z
      - .offset:         314
        .size:           2
        .value_kind:     hidden_remainder_x
      - .offset:         316
        .size:           2
        .value_kind:     hidden_remainder_y
      - .offset:         318
        .size:           2
        .value_kind:     hidden_remainder_z
      - .offset:         336
        .size:           8
        .value_kind:     hidden_global_offset_x
      - .offset:         344
        .size:           8
        .value_kind:     hidden_global_offset_y
      - .offset:         352
        .size:           8
        .value_kind:     hidden_global_offset_z
      - .offset:         360
        .size:           2
        .value_kind:     hidden_grid_dims
      - .offset:         384
        .size:           8
        .value_kind:     hidden_multigrid_sync_arg
    .group_segment_fixed_size: 73728
    .kernarg_segment_align: 8
    .kernarg_segment_size: 552
    .language:       OpenCL C
    .language_version:
      - 2
      - 0
    .max_flat_workgroup_size: 256
    .name:           _Z14fwd_megakernel6Params
    .private_segment_fixed_size: 0
    .sgpr_count:     108
    .sgpr_spill_count: 60
    .symbol:         _Z14fwd_megakernel6Params.kd
    .uniform_work_group_size: 1
    .uses_dynamic_stack: false
    .vgpr_count:     256
    .vgpr_spill_count: 0
    .wavefront_size: 64
